# mixer unit loops: thread-0 ticket wait at the loop top (a full vmcnt(0) that also drained the previous unit's stores) removed; the atomic is older than loads every unit consumes; pre-header waits once
# speedup vs baseline: 1.0068x; 1.0068x over previous
; #define LBAR() do { asm volatile("s_waitcnt lgkmcnt(0)" ::: "memory"); __builtin_amdgcn_s_barrier(); asm volatile("" ::: "memory"); } while (0)
; template <int WHICH>
; __device__ void phase_mix_dyn(LAS unsigned char* lds, KP& P0, int l0) {
;     ...
;     if (tid0 == 0) { n1 = (int)__hip_atomic_fetch_add(ctr, 1u, __ATOMIC_RELAXED, __HIP_MEMORY_SCOPE_AGENT); n2 = (int)__hip_atomic_fetch_add(ctr, 1u, __ATOMIC_RELAXED, __HIP_MEMORY_SCOPE_AGENT); }
;     int u, un;
;     for (;;) {
;         if (tid0 == 0) { tick[0] = n1; tick[1] = n2; }
;         LBAR();
.LBB0_303:
	s_or_b64 exec, exec, s[6:7]
	s_waitcnt vmcnt(0)
	s_branch .LBB0_307

; #define LBAR() do { asm volatile("s_waitcnt lgkmcnt(0)" ::: "memory"); __builtin_amdgcn_s_barrier(); asm volatile("" ::: "memory"); } while (0)
; template <int WHICH>
; __device__ void phase_mix_dyn(LAS unsigned char* lds, KP& P0, int l0) {
;     ...
;     for (;;) {
;         if (tid0 == 0) { tick[0] = n1; tick[1] = n2; }
;         LBAR();
;         u = tick[0]; un = tick[1];
;         if (u >= 780) break;
;         if (tid0 == 0) { n1 = n2; n2 = (int)__hip_atomic_fetch_add(ctr, 1u, __ATOMIC_RELAXED, __HIP_MEMORY_SCOPE_AGENT); }
.LBB0_307:
	v_mov_b32_e32 v137, v139
	s_and_saveexec_b64 s[6:7], s[40:41]
	s_cbranch_execz .LBB0_309
	v_mov_b32_e32 v136, v140
	v_readlane_b32 s12, v255, 7
	s_nop 1
	v_mov_b32_e32 v0, s12
	v_readlane_b32 s12, v255, 8
	ds_write_b32 v0, v137
	s_nop 0
	v_mov_b32_e32 v0, s12
	ds_write_b32 v0, v136

; #define LBAR() do { asm volatile("s_waitcnt lgkmcnt(0)" ::: "memory"); __builtin_amdgcn_s_barrier(); asm volatile("" ::: "memory"); } while (0)
; template <int WHICH>
; __device__ void phase_mix_dyn(LAS unsigned char* lds, KP& P0, int l0) {
;     ...
;     if (tid0 == 0) { n1 = (int)__hip_atomic_fetch_add(ctr, 1u, __ATOMIC_RELAXED, __HIP_MEMORY_SCOPE_AGENT); n2 = (int)__hip_atomic_fetch_add(ctr, 1u, __ATOMIC_RELAXED, __HIP_MEMORY_SCOPE_AGENT); }
;     int u, un;
;     for (;;) {
;         if (tid0 == 0) { tick[0] = n1; tick[1] = n2; }
;         LBAR();
.LBB0_604:
	s_or_b64 exec, exec, s[20:21]
	s_waitcnt vmcnt(0)
	s_branch .LBB0_607

; #define LBAR() do { asm volatile("s_waitcnt lgkmcnt(0)" ::: "memory"); __builtin_amdgcn_s_barrier(); asm volatile("" ::: "memory"); } while (0)
; template <int WHICH>
; __device__ void phase_mix_dyn(LAS unsigned char* lds, KP& P0, int l0) {
;     ...
;     for (;;) {
;         if (tid0 == 0) { tick[0] = n1; tick[1] = n2; }
;         LBAR();
;         u = tick[0]; un = tick[1];
;         if (u >= 780) break;
;         if (tid0 == 0) { n1 = n2; n2 = (int)__hip_atomic_fetch_add(ctr, 1u, __ATOMIC_RELAXED, __HIP_MEMORY_SCOPE_AGENT); }
.LBB0_607:
	v_mov_b32_e32 v99, v101
	s_and_saveexec_b64 s[14:15], s[40:41]
	s_cbranch_execz .LBB0_609
	v_mov_b32_e32 v98, v102
	v_readlane_b32 s12, v255, 7
	s_nop 1
	v_mov_b32_e32 v0, s12
	v_readlane_b32 s12, v255, 8
	ds_write_b32 v0, v99
	s_nop 0
	v_mov_b32_e32 v0, s12
	ds_write_b32 v0, v98
